# chip-wide seam split too: arrive + record target at phase end, wait for the cross-XCC count right before the next phase's first cross-workgroup load
# speedup vs baseline: 1.0110x; 1.0110x over previous
.LBB0_29:
	s_lshl_b32 s0, s12, 5
	s_add_i32 s6, s0, s13
	s_cmp_lg_u32 s14, 0
	s_cselect_b64 s[0:1], -1, 0
	s_and_b64 s[0:1], s[0:1], exec
	s_cselect_b32 s8, s6, s3
	s_lshl_b32 s0, s8, 6
	s_and_b32 s0, s0, 0xfffff800
	s_add_i32 s1, s0, 0x800
	s_cmp_lg_u32 s14, 0
	s_cselect_b64 s[6:7], -1, 0
	s_and_b64 s[6:7], s[6:7], exec
	s_cselect_b32 s98, s1, 0x4000
	s_lshl_b32 s10, s62, 3
	s_cmp_lg_u32 s14, 0
	s_cselect_b64 s[6:7], -1, 0
	s_and_b64 s[6:7], s[6:7], exec
	s_cselect_b32 s64, 0x100, s10
	s_lshl_b32 s1, s8, 4
	s_and_b32 s1, s1, 0xfffffe00
	s_add_i32 s3, s1, 0x200
	s_cmp_lg_u32 s14, 0
	s_cselect_b64 s[6:7], -1, 0
	s_and_b64 s[6:7], s[6:7], exec
	s_cselect_b32 s99, s3, 0x1000
	s_lshl_b32 s3, s13, 3
	s_add_i32 s3, s3, s12
	s_cmp_lg_u32 s14, 0
	s_cselect_b64 s[6:7], -1, 0
	v_writelane_b32 v236, s6, 8
	s_mov_b32 s36, 2.0
	s_mov_b32 s88, 0x41900000
	v_writelane_b32 v236, s7, 9
	s_and_b64 s[6:7], s[6:7], exec
	s_cselect_b32 s7, s3, s2
	s_lshl_b32 s9, s8, 3
	s_add_u32 s2, s60, 0x5300000
	s_addc_u32 s3, s61, 0
	v_writelane_b32 v236, s2, 10
	s_mov_b32 s96, 0x41a00000
	s_mov_b32 s44, 0x42480000
	v_writelane_b32 v236, s3, 11
	s_add_u32 s2, s60, 0x7300000
	s_addc_u32 s3, s61, 0
	s_add_u32 s90, s60, 0xd300000
	s_addc_u32 s91, s61, 0
	s_add_u32 s92, s60, 0xf300000
	s_addc_u32 s93, s61, 0
	s_add_u32 s94, s60, 0x9300000
	v_writelane_b32 v236, s2, 12
	s_addc_u32 s95, s61, 0
	s_mov_b32 s84, 0x42000000
	v_writelane_b32 v236, s3, 13
	s_add_u32 s2, s60, 0x100000
	s_addc_u32 s3, s61, 0
	v_writelane_b32 v236, s2, 14
	v_mbcnt_lo_u32_b32 v0, -1, 0
	v_mov_b32_e32 v97, 0
	v_writelane_b32 v236, s3, 15
	s_add_u32 s2, s74, 0xb000
	s_addc_u32 s3, s75, 0
	v_writelane_b32 v236, s2, 16
	v_mov_b32_e32 v153, 0x358637bd
	v_mov_b32_e32 v154, 0x260
	v_writelane_b32 v236, s3, 17
	s_add_u32 s2, s60, 0x3d80000
	s_addc_u32 s3, s61, 0
	v_writelane_b32 v236, s2, 18
	s_mov_b32 s37, 0x40400000
	s_mov_b32 s89, 0x41980000
	v_writelane_b32 v236, s3, 19
	s_add_u32 s2, s60, 0x2200000
	s_addc_u32 s3, s61, 0
	v_writelane_b32 v236, s2, 20
	s_mov_b32 s97, 0x41a80000
	s_mov_b32 s45, 0x424c0000
	v_writelane_b32 v236, s3, 21
	s_add_u32 s2, s74, 0x9000
	s_addc_u32 s3, s75, 0
	v_writelane_b32 v236, s2, 22
	s_mov_b32 s85, 0x42040000
	v_mov_b32_e32 v155, 1
	v_writelane_b32 v236, s3, 23
	s_add_u32 s2, s60, 0x5100000
	s_addc_u32 s3, s61, 0
	v_writelane_b32 v236, s2, 24
	v_mbcnt_hi_u32_b32 v156, -1, v0
	v_mov_b32_e32 v157, 0x42800000
	v_writelane_b32 v236, s3, 25
	s_add_u32 s2, s60, 0x4f00000
	s_addc_u32 s3, s61, 0
	v_writelane_b32 v236, s2, 26
	v_mov_b32_e32 v158, 0xff800000
	s_nop 0
	v_writelane_b32 v236, s3, 27
	s_add_u32 s2, s74, 0x7000
	s_addc_u32 s3, s75, 0
	v_writelane_b32 v236, s2, 28
	s_nop 1
	v_writelane_b32 v236, s3, 29
	s_add_u32 s2, s60, 0x3800000
	s_addc_u32 s3, s61, 0
	v_writelane_b32 v236, s2, 30
	s_nop 1
	v_writelane_b32 v236, s3, 31
	s_add_u32 s2, s60, 0x1700000
	s_addc_u32 s3, s61, 0
	s_add_u32 s20, s60, 0xb300000
	v_writelane_b32 v236, s2, 32
	s_addc_u32 s21, s61, 0
	s_nop 0
	v_writelane_b32 v236, s3, 33
	s_add_u32 s2, s60, 0x4d00000
	s_addc_u32 s3, s61, 0
	v_writelane_b32 v236, s2, 34
	s_nop 1
	v_writelane_b32 v236, s3, 35
	s_add_u32 s2, s60, 0x4b00000
	s_addc_u32 s3, s61, 0
	v_writelane_b32 v236, s2, 36
	s_nop 1
	v_writelane_b32 v236, s3, 37
	s_add_u32 s2, s74, 0x5000
	s_addc_u32 s3, s75, 0
	v_writelane_b32 v236, s2, 38
	s_nop 1
	v_writelane_b32 v236, s3, 39
	s_add_u32 s2, s60, 0x3280000
	s_addc_u32 s3, s61, 0
	v_writelane_b32 v236, s2, 40
	s_nop 1
	v_writelane_b32 v236, s3, 41
	s_add_u32 s2, s60, 0xc00000
	s_addc_u32 s3, s61, 0
	v_writelane_b32 v236, s2, 42
	s_nop 1
	v_writelane_b32 v236, s3, 43
	s_add_u32 s2, s74, 0x3000
	s_addc_u32 s3, s75, 0
	v_writelane_b32 v236, s2, 44
	s_nop 1
	v_writelane_b32 v236, s3, 45
	s_add_u32 s2, s60, 0x4900000
	s_addc_u32 s3, s61, 0
	v_writelane_b32 v236, s2, 46
	s_nop 1
	v_writelane_b32 v236, s3, 47
	s_add_u32 s2, s60, 0x4300000
	s_addc_u32 s3, s61, 0
	v_writelane_b32 v236, s2, 48
	s_nop 1
	v_writelane_b32 v236, s3, 49
	s_add_u32 s2, s74, 0x1000
	s_addc_u32 s3, s75, 0
	v_writelane_b32 v236, s2, 50
	s_nop 1
	v_writelane_b32 v236, s3, 51
	s_add_u32 s2, s60, 0x2d00000
	s_addc_u32 s3, s61, 0
	v_writelane_b32 v236, s2, 52
	s_nop 1
	v_writelane_b32 v236, s3, 53
	s_add_u32 s2, s74, 0x2000
	s_addc_u32 s3, s75, 0
	v_writelane_b32 v236, s2, 54
	s_cmp_lg_u64 s[74:75], 0
	s_nop 0
	v_writelane_b32 v236, s3, 55
	s_cselect_b64 s[2:3], -1, 0
	v_writelane_b32 v236, s2, 56
	s_cmpk_eq_i32 s62, 0x100
	s_nop 0
	v_writelane_b32 v236, s3, 57
	s_cselect_b64 s[2:3], -1, 0
	v_writelane_b32 v236, s2, 58
	s_cmpk_lg_i32 s62, 0x100
	s_nop 0
	v_writelane_b32 v236, s3, 59
	s_cselect_b64 s[2:3], -1, 0
	v_writelane_b32 v236, s2, 60
	s_nop 1
	v_writelane_b32 v236, s3, 61
	s_add_u32 s2, s72, 0xb00000
	s_addc_u32 s3, s73, 0
	v_writelane_b32 v236, s2, 62
	s_nop 1
	v_writelane_b32 v236, s3, 63
	s_add_u32 s2, s70, 0x1600000
	s_addc_u32 s3, s71, 0
	v_writelane_b32 v235, s2, 0
	v_readlane_b32 s24, v236, 0
	v_readlane_b32 s30, v236, 6
	v_writelane_b32 v235, s3, 1
	s_add_u32 s2, s74, 0x4000
	s_addc_u32 s3, s75, 0
	v_writelane_b32 v235, s2, 2
	v_readlane_b32 s31, v236, 7
	v_readlane_b32 s25, v236, 1
	v_writelane_b32 v235, s3, 3
	s_add_u32 s2, s74, 0x8000
	s_addc_u32 s3, s75, 0
	v_writelane_b32 v235, s2, 4
	v_readlane_b32 s26, v236, 2
	v_readlane_b32 s27, v236, 3
	v_writelane_b32 v235, s3, 5
	s_add_u32 s2, s72, 0x1600000
	s_addc_u32 s3, s73, 0
	v_writelane_b32 v235, s2, 6
	v_readlane_b32 s28, v236, 4
	v_readlane_b32 s29, v236, 5
	v_writelane_b32 v235, s3, 7
	s_add_u32 s2, s70, 0x2c00000
	s_addc_u32 s3, s71, 0
	v_writelane_b32 v235, s2, 8
	s_mov_b32 s24, 0x40c00000
	s_mov_b32 s26, 0x42400000
	v_writelane_b32 v235, s3, 9
	s_add_u32 s2, s74, 0x6000
	s_addc_u32 s3, s75, 0
	v_writelane_b32 v235, s2, 10
	s_cmp_lg_u64 s[82:83], 0
	s_mov_b32 s28, 0x42180000
	v_writelane_b32 v235, s3, 11
	s_cselect_b64 s[2:3], -1, 0
	v_writelane_b32 v235, s2, 12
	s_mov_b32 s25, 0x40e00000
	s_mov_b32 s27, 0x42440000
	v_writelane_b32 v235, s3, 13
	s_add_u32 s2, s72, 0x2100000
	s_addc_u32 s3, s73, 0
	v_writelane_b32 v235, s2, 14
	s_mov_b32 s29, 0x421c0000
	s_nop 0
	v_writelane_b32 v235, s3, 15
	s_add_u32 s2, s70, 0x4200000
	s_addc_u32 s3, s71, 0
	v_writelane_b32 v235, s2, 16
	s_nop 1
	v_writelane_b32 v235, s3, 17
	s_add_u32 s2, s74, 0xa000
	s_addc_u32 s3, s75, 0
	v_writelane_b32 v235, s2, 18
	s_cmp_lg_u64 s[30:31], 0
	s_mov_b32 s30, 0x41800000
	v_writelane_b32 v235, s3, 19
	s_cselect_b64 s[2:3], -1, 0
	v_writelane_b32 v235, s2, 20
	s_mov_b32 s31, 0x41880000
	s_nop 0
	v_writelane_b32 v235, s3, 21
	s_add_u32 s2, s60, 0x12c00000
	v_writelane_b32 v235, s2, 22
	s_addc_u32 s2, s61, 0
	s_cmp_eq_u64 s[68:69], 0
	v_writelane_b32 v235, s2, 23
	s_cselect_b64 s[2:3], -1, 0
	s_cmp_lg_u64 s[68:69], 0
	s_cselect_b64 s[14:15], -1, 0
	v_writelane_b32 v235, s14, 24
	s_cmpk_lt_i32 s8, 0x100
	s_nop 0
	v_writelane_b32 v235, s15, 25
	v_writelane_b32 v235, s8, 26
	s_cselect_b64 s[14:15], -1, 0
	v_writelane_b32 v235, s14, 27
	s_and_b32 s6, s9, 0xf8
	s_or_b32 s1, s1, s6
	v_writelane_b32 v235, s15, 28
	v_writelane_b32 v235, s1, 29
	s_or_b32 s0, s0, s6
	v_writelane_b32 v235, s0, 30
	s_ashr_i32 s0, s7, 31
	v_writelane_b32 v235, s0, 31
	s_lshr_b32 s0, s0, 29
	s_add_i32 s0, s7, s0
	s_ashr_i32 s1, s0, 3
	s_and_b32 s0, s0, -8
	s_sub_i32 s8, s7, s0
	s_ashr_i32 s0, s62, 31
	v_writelane_b32 v235, s1, 32
	s_cmpk_gt_i32 s7, 0x7f
	v_writelane_b32 v235, s0, 33
	s_cselect_b64 s[0:1], -1, 0
	v_writelane_b32 v235, s0, 34
	s_nop 1
	v_writelane_b32 v235, s1, 35
	s_lshl_b32 s0, s7, 3
	s_addk_i32 s0, 0xfc00
	s_add_u32 s14, s60, 0x12b00200
	s_addc_u32 s15, s61, 0
	s_add_u32 s52, s60, 0x12b00400
	s_addc_u32 s53, s61, 0
	s_add_u32 s54, s60, 0x12b00500
	s_addc_u32 s55, s61, 0
	s_add_u32 s66, s60, 0x12b00600
	s_addc_u32 s67, s61, 0
	s_add_u32 s16, s60, 0x12b00700
	s_addc_u32 s17, s61, 0
	s_add_u32 s18, s60, 0x12b00800
	s_addc_u32 s19, s61, 0
	s_add_u32 s22, s60, 0x12b00900
	v_writelane_b32 v235, s7, 36
	s_addc_u32 s23, s61, 0
	v_writelane_b32 v235, s0, 37
	s_add_u32 s0, s60, 0x12b00a00
	s_addc_u32 s1, s61, 0
	v_writelane_b32 v235, s0, 38
	s_nop 1
	v_writelane_b32 v235, s1, 39
	s_add_u32 s0, s60, 0x12b00b00
	s_addc_u32 s1, s61, 0
	v_writelane_b32 v235, s0, 40
	s_nop 1
	v_writelane_b32 v235, s1, 41
	s_add_u32 s0, s60, 0x12b00c00
	s_addc_u32 s1, s61, 0
	v_writelane_b32 v235, s0, 42
	s_nop 1
	v_writelane_b32 v235, s1, 43
	s_add_u32 s0, s60, 0x12b00d00
	s_addc_u32 s1, s61, 0
	v_writelane_b32 v235, s0, 44
	s_nop 1
	v_writelane_b32 v235, s1, 45
	s_add_u32 s0, s60, 0x12b00e00
	s_addc_u32 s1, s61, 0
	v_writelane_b32 v235, s0, 46
	s_nop 1
	v_writelane_b32 v235, s1, 47
	s_add_u32 s0, s60, 0x12b00f00
	s_addc_u32 s1, s61, 0
	v_writelane_b32 v235, s0, 48
	s_nop 1
	v_writelane_b32 v235, s1, 49
	s_add_u32 s0, s60, 0x12b01000
	s_addc_u32 s1, s61, 0
	v_writelane_b32 v235, s0, 50
	s_nop 1
	v_writelane_b32 v235, s1, 51
	s_add_u32 s0, s60, 0x12b01100
	s_addc_u32 s1, s61, 0
	v_writelane_b32 v235, s0, 52
	s_nop 1
	v_writelane_b32 v235, s1, 53
	s_add_u32 s0, s60, 0x12b01200
	s_addc_u32 s1, s61, 0
	v_writelane_b32 v235, s0, 54
	s_nop 1
	v_writelane_b32 v235, s1, 55
	s_add_u32 s0, s60, 0x12b01300
	s_addc_u32 s1, s61, 0
	v_writelane_b32 v235, s0, 56
	s_cmp_eq_u32 s50, 15
	s_nop 0
	v_writelane_b32 v235, s1, 57
	s_cselect_b64 s[0:1], -1, 0
	v_writelane_b32 v235, s0, 58
	s_cmp_eq_u32 s50, 14
	s_nop 0
	v_writelane_b32 v235, s1, 59
	s_cselect_b64 s[0:1], -1, 0
	v_writelane_b32 v235, s0, 60
	s_cmp_eq_u32 s50, 13
	s_nop 0
	v_writelane_b32 v235, s1, 61
	s_cselect_b64 s[0:1], -1, 0
	v_writelane_b32 v235, s0, 62
	s_cmp_eq_u32 s50, 12
	s_nop 0
	v_writelane_b32 v235, s1, 63
	s_cselect_b64 s[0:1], -1, 0
	v_writelane_b32 v234, s0, 0
	s_cmp_eq_u32 s50, 11
	s_nop 0
	v_writelane_b32 v234, s1, 1
	s_cselect_b64 s[0:1], -1, 0
	v_writelane_b32 v234, s0, 2
	s_cmp_eq_u32 s50, 10
	s_nop 0
	v_writelane_b32 v234, s1, 3
	s_cselect_b64 s[0:1], -1, 0
	v_writelane_b32 v234, s0, 4
	s_cmp_eq_u32 s50, 9
	s_nop 0
	v_writelane_b32 v234, s1, 5
	s_cselect_b64 s[0:1], -1, 0
	v_writelane_b32 v234, s0, 6
	s_cmp_eq_u32 s50, 8
	s_nop 0
	v_writelane_b32 v234, s1, 7
	s_cselect_b64 s[0:1], -1, 0
	v_writelane_b32 v234, s0, 8
	s_cmp_eq_u32 s50, 7
	s_nop 0
	v_writelane_b32 v234, s1, 9
	s_cselect_b64 s[0:1], -1, 0
	v_writelane_b32 v234, s0, 10
	s_cmp_eq_u32 s50, 6
	s_nop 0
	v_writelane_b32 v234, s1, 11
	s_cselect_b64 s[0:1], -1, 0
	v_writelane_b32 v234, s0, 12
	s_cmp_eq_u32 s50, 5
	s_nop 0
	v_writelane_b32 v234, s1, 13
	s_cselect_b64 s[0:1], -1, 0
	v_writelane_b32 v234, s0, 14
	s_cmp_eq_u32 s50, 4
	s_nop 0
	v_writelane_b32 v234, s1, 15
	s_cselect_b64 s[0:1], -1, 0
	v_writelane_b32 v234, s0, 16
	s_cmp_eq_u32 s50, 3
	s_nop 0
	v_writelane_b32 v234, s1, 17
	s_cselect_b64 s[0:1], -1, 0
	v_writelane_b32 v234, s0, 18
	s_cmp_eq_u32 s50, 2
	s_nop 0
	v_writelane_b32 v234, s1, 19
	s_cselect_b64 s[0:1], -1, 0
	v_writelane_b32 v234, s0, 20
	s_cmp_eq_u32 s50, 1
	s_nop 0
	v_writelane_b32 v234, s1, 21
	s_cselect_b64 s[0:1], -1, 0
	v_writelane_b32 v234, s0, 22
	s_cmp_eq_u32 s50, 0
	s_nop 0
	v_writelane_b32 v234, s1, 23
	s_cselect_b64 s[0:1], -1, 0
	v_writelane_b32 v234, s0, 24
	s_nop 1
	v_writelane_b32 v234, s1, 25
	s_lshl_b32 s0, s50, 8
	s_add_u32 s0, s4, s0
	s_addc_u32 s1, s5, 0
	s_add_u32 s6, s0, 0x1400
	s_addc_u32 s7, s1, 0
	v_writelane_b32 v234, s6, 26
	s_add_u32 s0, s0, 0x2400
	s_addc_u32 s1, s1, 0
	v_writelane_b32 v234, s7, 27
	v_writelane_b32 v234, s0, 28
	s_mov_b64 s[50:51], s[14:15]
	s_mov_b32 s14, 4.0
	v_writelane_b32 v234, s1, 29
	s_add_u32 s0, s60, 0x12b03400
	s_addc_u32 s1, s61, 0
	v_writelane_b32 v234, s0, 30
	s_mov_b32 s15, 0x40a00000
	s_nop 0
	v_writelane_b32 v234, s1, 31
	s_add_u32 s0, s60, 0x12b03500
	s_addc_u32 s1, s61, 0
	s_lshl_b32 s6, s12, 6
	v_writelane_b32 v234, s0, 32
	s_add_i32 s46, s6, 0x1000
	s_mov_b64 s[12:13], 0x80
	v_writelane_b32 v234, s1, 33
	s_lshl_b64 s[0:1], s[46:47], 2
	s_add_u32 s0, s4, s0
	s_addc_u32 s1, s5, s1
	v_writelane_b32 v234, s0, 34
	s_add_i32 s46, s6, 0x1400
	s_nop 0
	v_writelane_b32 v234, s1, 35
	s_lshl_b64 s[0:1], s[46:47], 2
	s_add_u32 s0, s4, s0
	s_addc_u32 s1, s5, s1
	v_writelane_b32 v234, s0, 36
	s_ashr_i32 s11, s10, 31
	s_nop 0
	v_writelane_b32 v234, s1, 37
	s_mul_i32 s0, s63, s62
	s_mul_i32 s0, s0, s33
	v_writelane_b32 v234, s0, 38
	v_writelane_b32 v234, s8, 39
	s_lshr_b32 s0, s8, 31
	v_writelane_b32 v234, s0, 40
	s_add_i32 s0, s9, s10
	v_writelane_b32 v234, s0, 41
	s_lshl_b64 s[0:1], s[10:11], 2
	v_writelane_b32 v234, s0, 42
	s_mov_b32 s33, 0xf800000
	s_nop 0
	v_writelane_b32 v234, s1, 43
	s_lshl_b64 s[0:1], s[10:11], 11
	v_writelane_b32 v234, s0, 44
	s_nop 1
	v_writelane_b32 v234, s1, 45
	s_add_u32 s0, s68, 0x800
	v_writelane_b32 v234, s0, 46
	v_writelane_b32 v234, s68, 47
	s_addc_u32 s0, s69, 0
	s_nop 0
	v_writelane_b32 v234, s69, 48
	v_writelane_b32 v234, s70, 49
	v_writelane_b32 v234, s71, 50
	v_writelane_b32 v234, s72, 51
	v_writelane_b32 v234, s73, 52
	v_writelane_b32 v234, s74, 53
	v_writelane_b32 v234, s75, 54
	v_writelane_b32 v234, s76, 55
	v_writelane_b32 v234, s77, 56
	v_writelane_b32 v234, s78, 57
	v_writelane_b32 v234, s79, 58
	v_writelane_b32 v234, s80, 59
	v_writelane_b32 v234, s81, 60
	v_writelane_b32 v234, s82, 61
	v_writelane_b32 v234, s83, 62
	v_writelane_b32 v234, s0, 63
	s_lshl_b64 s[0:1], s[10:11], 12
	v_writelane_b32 v233, s0, 0
	s_mov_b32 s70, s9
	s_mov_b64 s[68:69], s[10:11]
	v_writelane_b32 v233, s1, 1
	s_add_u32 s0, s60, 0xb300080
	v_writelane_b32 v233, s0, 2
	s_addc_u32 s0, s61, 0
	v_writelane_b32 v233, s0, 3
	s_add_u32 s0, s60, 0x9320000
	s_mov_b64 s[4:5], s[56:57]
	v_writelane_b32 v233, s0, 4
	s_mov_b64 s[6:7], s[58:59]
	s_mov_b64 s[8:9], s[60:61]
	s_mov_b32 s10, s62
	v_writelane_b32 v233, s4, 5
	s_addc_u32 s0, s61, 0
	s_ashr_i32 s65, s64, 31
	v_writelane_b32 v233, s5, 6
	v_writelane_b32 v233, s6, 7
	v_writelane_b32 v233, s7, 8
	v_writelane_b32 v233, s8, 9
	v_writelane_b32 v233, s9, 10
	v_writelane_b32 v233, s10, 11
	v_writelane_b32 v233, s11, 12
	v_writelane_b32 v233, s0, 13
	s_lshl_b32 s0, s64, 2
	v_writelane_b32 v233, s0, 14
	s_lshl_b32 s0, s64, 9
	v_writelane_b32 v233, s0, 15
	s_add_i32 s0, 0, 0x20040
	v_writelane_b32 v233, s0, 16
	s_add_i32 s0, 0, 0x20044
	v_writelane_b32 v233, s0, 17
	s_lshl_b64 s[8:9], s[64:65], 2
	v_writelane_b32 v233, s8, 18
	s_mov_b32 s1, 0
	s_mov_b32 s0, s68
	v_writelane_b32 v233, s9, 19
	s_lshl_b64 s[8:9], s[64:65], 11
	v_writelane_b32 v233, s8, 20
	s_mov_b64 s[76:77], s[16:17]
	s_mov_b64 s[78:79], s[18:19]
	v_writelane_b32 v233, s9, 21
	s_lshl_b64 s[8:9], s[64:65], 12
	v_writelane_b32 v233, s8, 22
	s_mov_b64 s[82:83], s[22:23]
	s_mov_b32 s6, 0x41b00000
	v_writelane_b32 v233, s9, 23
	s_lshl_b64 s[8:9], s[64:65], 6
	v_writelane_b32 v233, s8, 24
	s_mov_b32 s18, 0x42580000
	s_mov_b32 s22, 0x42500000
	v_writelane_b32 v233, s9, 25
	v_writelane_b32 v233, s86, 26
	s_mov_b32 s4, 0x42100000
	s_mov_b32 s10, 0x42080000
	v_writelane_b32 v233, s87, 27
	v_writelane_b32 v233, s98, 28
	v_writelane_b32 v233, s0, 29
	s_mov_b32 s7, 0x41b80000
	s_mov_b32 s19, 0x425c0000
	v_writelane_b32 v233, s1, 30
	s_mov_b32 s0, s64
	v_writelane_b32 v233, s0, 31
	s_mov_b32 s23, 0x42540000
	s_mov_b32 s5, 0x42140000
	v_writelane_b32 v233, s1, 32
	v_writelane_b32 v233, s99, 33
	v_writelane_b32 v233, s70, 34
	v_writelane_b32 v233, s50, 35
	s_mov_b32 s11, 0x420c0000
	s_movk_i32 s81, 0x7fff
	v_writelane_b32 v233, s51, 36
	v_writelane_b32 v233, s52, 37
	s_mov_b32 s71, 0xffff0000
	s_movk_i32 s80, 0x48
	v_writelane_b32 v233, s53, 38
	v_writelane_b32 v233, s54, 39
	s_mov_b64 s[16:17], 0x20000
	s_nop 0
	v_writelane_b32 v233, s55, 40
	v_writelane_b32 v233, s66, 41
	s_nop 1
	v_writelane_b32 v233, s67, 42
	v_writelane_b32 v233, s76, 43
	s_nop 1
	v_writelane_b32 v233, s77, 44
	v_writelane_b32 v233, s78, 45
	s_nop 1
	v_writelane_b32 v233, s79, 46
	v_writelane_b32 v233, s82, 47
	s_nop 1
	v_writelane_b32 v233, s83, 48
	s_mov_b32 s0, 0
	v_writelane_b32 v232, s0, 58
	s_mov_b32 s0, 0
	v_writelane_b32 v232, s0, 59
	s_branch .LBB0_31

.LBB0_270:
	s_and_b64 vcc, exec, s[0:1]
	s_cbranch_vccz .LBB0_305
	v_readlane_b32 vcc_lo, v232, 59
	s_cmp_eq_u32 vcc_lo, 0
	s_cbranch_scc1 .Lcb_done_a
	v_readfirstlane_b32 vcc_hi, v152
	s_cmp_lt_u32 vcc_hi, 64
	s_cbranch_scc0 .Lcb_wait_a
	v_readlane_b32 s100, v234, 30
	v_readlane_b32 s101, v234, 31
	s_mov_b32 m0, 0
	s_nop 4
.Lcb_poll_a:
	global_load_dword v210, v97, s[100:101] sc1
	s_waitcnt vmcnt(0)
	v_readfirstlane_b32 vcc_lo, v210
	v_readfirstlane_b32 vcc_hi, v211
	s_cmp_ge_u32 vcc_lo, vcc_hi
	s_cbranch_scc1 .Lcb_got_a
	s_sleep 1
	s_add_u32 m0, m0, 1
	s_cmp_lt_u32 m0, 0x40000
	s_cbranch_scc1 .Lcb_poll_a

.Lcb_wait_a:
	s_mov_b32 vcc_lo, 0
	v_writelane_b32 v232, vcc_lo, 59
	s_barrier
.Lcb_done_a:
	v_readlane_b32 s48, v236, 0
	v_lshlrev_b32_e32 v2, 2, v159
	v_readlane_b32 s52, v236, 4
	v_readlane_b32 s53, v236, 5
	s_nop 4
	global_load_dword v0, v2, s[52:53]
	global_load_dword v1, v2, s[52:53] offset:256
	v_and_b32_e32 v4, 64, v156
	v_add_u32_e32 v4, 64, v4
	v_xor_b32_e32 v5, 1, v156
	v_cmp_lt_i32_e32 vcc, v5, v4
	v_readlane_b32 s0, v235, 27
	v_readlane_b32 s1, v235, 28
	v_cndmask_b32_e32 v5, v156, v5, vcc
	v_lshlrev_b32_e32 v161, 2, v5
	v_readlane_b32 s49, v236, 1
	v_readlane_b32 s50, v236, 2
	v_readlane_b32 s51, v236, 3
	v_readlane_b32 s54, v236, 6
	v_readlane_b32 s55, v236, 7
	s_waitcnt vmcnt(0) lgkmcnt(0)
	v_mul_f32_e32 v3, v0, v1
	ds_bpermute_b32 v3, v161, v3
	s_waitcnt lgkmcnt(0)
	v_fmac_f32_e32 v3, v0, v1
	v_xor_b32_e32 v0, 2, v156
	v_cmp_lt_i32_e32 vcc, v0, v4
	v_xor_b32_e32 v1, 4, v156
	s_nop 0
	v_cndmask_b32_e32 v0, v156, v0, vcc
	v_lshlrev_b32_e32 v162, 2, v0
	ds_bpermute_b32 v0, v162, v3
	v_cmp_lt_i32_e32 vcc, v1, v4
	s_waitcnt lgkmcnt(0)
	v_add_f32_e32 v0, v3, v0
	global_load_dword v3, v2, s[52:53] offset:512
	s_nop 0
	global_load_dword v2, v2, s[52:53] offset:768
	v_cndmask_b32_e32 v1, v156, v1, vcc
	v_lshlrev_b32_e32 v163, 2, v1
	ds_bpermute_b32 v1, v163, v0
	s_waitcnt lgkmcnt(0)
	v_add_f32_e32 v0, v0, v1
	v_xor_b32_e32 v1, 8, v156
	v_cmp_lt_i32_e32 vcc, v1, v4
	s_nop 1
	v_cndmask_b32_e32 v1, v156, v1, vcc
	v_lshlrev_b32_e32 v164, 2, v1
	ds_bpermute_b32 v1, v164, v0
	s_waitcnt lgkmcnt(0)
	v_add_f32_e32 v0, v0, v1
	v_xor_b32_e32 v1, 16, v156
	v_cmp_lt_i32_e32 vcc, v1, v4
	s_nop 1
	v_cndmask_b32_e32 v1, v156, v1, vcc
	v_lshlrev_b32_e32 v165, 2, v1
	ds_bpermute_b32 v1, v165, v0
	s_waitcnt lgkmcnt(0)
	v_add_f32_e32 v0, v0, v1
	v_xor_b32_e32 v1, 32, v156
	v_cmp_lt_i32_e32 vcc, v1, v4
	s_waitcnt vmcnt(0)
	v_mul_f32_e32 v4, v3, v2
	ds_bpermute_b32 v4, v161, v4
	v_cndmask_b32_e32 v1, v156, v1, vcc
	v_lshlrev_b32_e32 v166, 2, v1
	ds_bpermute_b32 v1, v166, v0
	s_andn2_b64 vcc, exec, s[0:1]
	s_waitcnt lgkmcnt(1)
	v_fmac_f32_e32 v4, v3, v2
	ds_bpermute_b32 v2, v162, v4
	s_waitcnt lgkmcnt(0)
	v_add_f32_e32 v2, v4, v2
	ds_bpermute_b32 v3, v163, v2
	s_waitcnt lgkmcnt(0)
	v_add_f32_e32 v2, v2, v3
	ds_bpermute_b32 v3, v164, v2
	s_waitcnt lgkmcnt(0)
	v_add_f32_e32 v2, v2, v3
	ds_bpermute_b32 v3, v165, v2
	s_waitcnt lgkmcnt(0)
	v_add_f32_e32 v2, v2, v3
	ds_bpermute_b32 v3, v166, v2
	s_cbranch_vccnz .LBB0_305
	v_add_f32_e32 v0, v0, v1
	s_waitcnt lgkmcnt(0)
	v_add_f32_e32 v1, v2, v3
	v_mul_f32_e32 v0, 0x3fb8aa3b, v0
	v_mul_f32_e32 v1, 0x3fb8aa3b, v1
	v_exp_f32_e32 v0, v0
	v_exp_f32_e32 v1, v1
	s_mov_b32 s58, s76
	s_mov_b64 s[56:57], s[78:79]
	v_readlane_b32 s76, v235, 26
	v_sub_f32_e32 v0, v0, v1
	v_add_f32_e32 v167, 0x3eb60549, v0
	s_branch .LBB0_274

.LBB0_307:
	v_readlane_b32 s0, v232, 6
	s_cmp_gt_i32 s0, 1
	s_mov_b64 s[0:1], -1
	s_cbranch_scc0 .LBB0_316
	v_readlane_b32 s0, v235, 29
	v_readlane_b32 s1, v232, 21
	s_add_i32 s8, s0, s1
	v_readlane_b32 s0, v236, 8
	v_readlane_b32 s1, v236, 9
	s_and_b64 s[0:1], s[0:1], exec
	s_cselect_b32 s8, s8, s76
	s_cmp_ge_i32 s8, s99
	s_cbranch_scc1 .LBB0_315
	v_readlane_b32 vcc_lo, v232, 59
	s_cmp_eq_u32 vcc_lo, 0
	s_cbranch_scc1 .Lcb_done_c
	v_readfirstlane_b32 vcc_hi, v152
	s_cmp_lt_u32 vcc_hi, 64
	s_cbranch_scc0 .Lcb_wait_c
	v_readlane_b32 s100, v234, 30
	v_readlane_b32 s101, v234, 31
	s_mov_b32 m0, 0
	s_nop 4

.Lcb_done_c:
	v_lshlrev_b32_e32 v76, 3, v159
	s_lshl_b32 s9, s8, 2
	s_lshl_b32 s46, s8, 9
	s_branch .LBB0_312

.Lsb_done_g:
	v_readlane_b32 vcc_lo, v232, 59
	s_cmp_eq_u32 vcc_lo, 0
	s_cbranch_scc1 .Lcb_done_g
	v_readfirstlane_b32 vcc_hi, v152
	s_cmp_lt_u32 vcc_hi, 64
	s_cbranch_scc0 .Lcb_wait_g
	v_readlane_b32 s100, v234, 30
	v_readlane_b32 s101, v234, 31
	s_mov_b32 m0, 0
	s_nop 4

.LBB0_531:
	s_or_b64 exec, exec, s[8:9]
	v_cvt_f32_u32_e32 v4, v2
	s_waitcnt vmcnt(0)
	v_readfirstlane_b32 s8, v3
	v_sub_u32_e32 v3, 0, v2
	v_rcp_iflag_f32_e32 v4, v4
	v_add_u32_e32 v5, s8, v1
	v_mul_f32_e32 v4, 0x4f7ffffe, v4
	v_cvt_u32_f32_e32 v4, v4
	v_mul_lo_u32 v1, v3, v4
	v_mul_hi_u32 v1, v4, v1
	v_add_u32_e32 v1, v4, v1
	v_mul_hi_u32 v1, v5, v1
	v_mul_lo_u32 v3, v1, v2
	v_sub_u32_e32 v3, v5, v3
	v_add_u32_e32 v4, 1, v1
	v_cmp_ge_u32_e32 vcc, v3, v2
	s_nop 1
	v_cndmask_b32_e32 v1, v1, v4, vcc
	v_sub_u32_e32 v4, v3, v2
	v_cndmask_b32_e32 v3, v3, v4, vcc
	v_add_u32_e32 v4, 1, v1
	v_cmp_ge_u32_e32 vcc, v3, v2
	v_add_u32_e32 v3, 1, v5
	s_nop 0
	v_cndmask_b32_e32 v1, v1, v4, vcc
	v_mul_lo_u32 v4, v2, v1
	v_add_u32_e32 v2, v4, v2
	v_cmp_ne_u32_e32 vcc, v3, v2
	s_and_saveexec_b64 s[8:9], vcc
	s_xor_b64 s[8:9], exec, s[8:9]
	s_cbranch_execz .LBB0_545
	s_waitcnt lgkmcnt(0)
	v_add_u32_e32 v3, 1, v1
	v_mul_lo_u32 v211, v3, v0
.LBB0_545:
	s_andn2_saveexec_b64 s[8:9], s[8:9]
	s_cbranch_execz .LBB0_565
	s_mov_b64 s[8:9], exec
	buffer_wbl2 sc1
	s_waitcnt lgkmcnt(0)
	s_waitcnt vmcnt(0)
	v_add_u32_e32 v3, 1, v1
	v_mul_lo_u32 v211, v3, v0
	v_mbcnt_lo_u32_b32 v1, s8, 0
	v_mbcnt_hi_u32_b32 v1, s9, v1
	v_cmp_eq_u32_e32 vcc, 0, v1
	s_and_saveexec_b64 s[34:35], vcc
	s_cbranch_execz .LBB0_548
	s_bcnt1_i32_b64 s8, s[8:9]
	v_mov_b32_e32 v2, s8
	v_readlane_b32 s8, v234, 30
	v_readlane_b32 s9, v234, 31
	s_nop 4
	global_atomic_add v97, v2, s[8:9]

.LBB0_565:
	s_or_b64 exec, exec, s[0:1]
	s_waitcnt lgkmcnt(0)
	s_mov_b32 s8, 1
	v_writelane_b32 v232, s8, 59
	s_mov_b64 s[0:1], -1
	s_branch .LBB0_586
